# select search: stage-2 positive-threshold update made branch-free and laid out to fall through into the next-probe code (one taken branch per pass)
# speedup vs baseline: 1.0092x; 1.0014x over previous
; __device__ __forceinline__ float keyval(unsigned k) { return __uint_as_float((k & 0x80000000u) ? (k ^ 0x80000000u) : ~k); }
; __device__ __forceinline__ unsigned valkey(float f) { const unsigned b = __float_as_uint(f); return b ^ ((unsigned)((int)b >> 31) | 0x80000000u); }
; __device__ __forceinline__ void select_query(const unsigned (&u)[64], unsigned vmax, int q, int b, int lane, unsigned* MASKb) {
;     ...
;             if (hi - lo <= 1u) { T = lo; exact = false; break; }
;             const float vlo = keyval(lo), vhi = keyval(hi);
;             const float frac = (it >= 9 && (it & 1)) ? 0.5f : Llo * __builtin_amdgcn_rcpf(Llo + Lhi);
;             unsigned mid = valkey(vlo + frac * (vhi - vlo));
;             if (mid <= lo) mid = lo + 1u;
;             if (mid >= hi) mid = hi - 1u;
;             mid = __builtin_amdgcn_readfirstlane(mid);
;             const int c = count_ge(u, mid, nblk);
;             if (c == 256) { T = mid; exact = true; break; }
;             if (c > 256) { lo = mid; Llo = __log2f((float)c) - L256; if (last == 1) Lhi *= 0.5f; last = 1; }
;             else { hi = mid; Lhi = L256 - __log2f(fmaxf((float)c, 0.5f)); if (last == 2) Llo *= 0.5f; last = 2; }
.Lsqa_red:
	v_add_u32_e32 v0, v0, v34
	s_nop 1
	v_add_u32_dpp v0, v0, v0 row_shr:1 row_mask:0xf bank_mask:0xf bound_ctrl:1
	s_nop 1
	v_add_u32_dpp v0, v0, v0 row_shr:2 row_mask:0xf bank_mask:0xf bound_ctrl:1
	s_nop 1
	v_add_u32_dpp v0, v0, v0 row_shr:4 row_mask:0xf bank_mask:0xf bound_ctrl:1
	s_nop 1
	v_add_u32_dpp v0, v0, v0 row_shr:8 row_mask:0xf bank_mask:0xf bound_ctrl:1
	s_nop 1
	v_add_u32_dpp v0, v0, v0 row_bcast:15 row_mask:0xa bank_mask:0xf
	s_nop 1
	v_add_u32_dpp v0, v0, v0 row_bcast:31 row_mask:0xc bank_mask:0xf
	s_nop 0
	v_readlane_b32 s24, v0, 63
	s_cmp_lg_u32 s21, 2
	s_cbranch_scc1 .Lsqa_disp
	s_cmp_lg_u32 s99, 0
	s_cbranch_scc1 .Lsqa_st2
	s_cmpk_eq_i32 s24, 0x100
	s_cbranch_scc1 .Lsqa_exact
	v_cvt_f32_u32_e32 v191, s24
	s_cmpk_gt_i32 s24, 0x100
	s_cselect_b64 vcc, -1, 0
	v_max_f32_e32 v191, 0.5, v191
	s_cselect_b32 s13, s14, s13
	s_cselect_b32 s12, s12, s14
	v_log_f32_e32 v191, v191
	s_cselect_b32 s98, s24, s98
	s_cselect_b32 s15, s15, s24
	s_cselect_b32 s26, 1, 2
	v_cndmask_b32_e32 v192, v192, v88, vcc
	v_cndmask_b32_e32 v193, v88, v193, vcc
	s_cmp_eq_u32 s23, s26
	s_cselect_b32 s27, 0x3f400000, 1.0
	s_mov_b32 s23, s26
	s_add_i32 s22, s22, 1
	v_add_f32_e32 v0, 0xc1000b88, v191
	v_sub_f32_e32 v34, 0x41000b88, v191
	v_mul_f32_e32 v203, s27, v36
	v_mul_f32_e32 v204, s27, v35
	v_cndmask_b32_e32 v35, v204, v0, vcc
	v_cndmask_b32_e32 v36, v34, v203, vcc
.Lsqa_next:
	s_sub_u32 s26, s12, s13
	s_cmp_lt_u32 s26, 2
	s_cbranch_scc1 .Lsqa_collapse
	s_sub_u32 s26, s98, s15
	s_cmp_le_u32 s26, 4
	s_cbranch_scc1 .Lsqa_endg
	s_cmp_eq_u32 s101, 0
	s_cbranch_scc1 .Lsqa_lin
	s_cmp_lt_i32 s22, 9
	s_cbranch_scc0 .Lsqa_lin
	v_add_f32_e32 v191, v35, v36
	v_sub_f32_e32 v34, v193, v192
	v_rcp_f32_e32 v191, v191
	s_lshl_b32 s26, s99, 31
	v_mul_f32_e32 v191, v35, v191
	v_fma_f32 v88, v191, v34, v192
	v_log_f32_e32 v0, v88
	s_nop 0
	v_mul_f32_e32 v0, 0x3f2aaaab, v0
	v_exp_f32_e32 v191, v0
	s_nop 0
	v_xor_b32_e32 v191, s26, v191

; __device__ __forceinline__ void select_query(const unsigned (&u)[64], unsigned vmax, int q, int b, int lane, unsigned* MASKb) {
;     ...
;         const int cpos = count_ge(u, K0 + 1u, nblk);
;         if (cpos == 256) { T = K0 + 1u; exact = true; done = true; }
;         else if (cpos > 256) { lo = K0 + 1u; Llo = __log2f((float)cpos) - L256; hi = kmax + 1u; Lhi = L256 + 1.f; }
.Lsqa_disp:
	s_cmp_eq_u32 s21, 2
	s_cbranch_scc1 .Lsqa_st2
	s_cmp_eq_u32 s21, 1
	s_cbranch_scc1 .Lsqa_st1
	s_cmpk_eq_i32 s24, 0x100
	s_cbranch_scc1 .Lsqa_exact
	s_cmpk_gt_i32 s24, 0x100
	s_cbranch_scc0 .Lsqa_s0lt
	s_mov_b32 s13, 0x80000001
	s_add_i32 s12, s19, 1
	s_mov_b32 s15, 0
	v_cvt_f32_u32_e32 v35, s24
	v_log_f32_e32 v35, v35
	v_mov_b32_e32 v36, 0x41200b88
	v_add_f32_e32 v35, 0xc1000b88, v35
	s_and_b32 s26, s12, 0x7fffffff
	s_bfe_u32 s27, s26, 0x80017
	s_sub_u32 s27, s27, 0x43
	s_cmp_lt_u32 s27, 0x79
	s_cselect_b32 s101, 1, 0
	v_sqrt_f32_e32 v193, s26
	v_mov_b32_e32 v192, 0
	v_mul_f32_e32 v193, s26, v193
	s_mov_b32 s98, s24
	s_mov_b32 s99, 0
	s_mov_b32 s22, 0
	s_mov_b32 s23, 0
	s_mov_b32 s21, 2
	s_branch .Lsqa_next

; __device__ __forceinline__ void select_query(const unsigned (&u)[64], unsigned vmax, int q, int b, int lane, unsigned* MASKb) {
;     ...
;             else { hi = mid; Lhi = L256 - __log2f(fmaxf((float)c, 0.5f)); if (last == 2) Llo *= 0.5f; last = 2; }
;             ++it;
.Lsqa_s2bj:
	s_mov_b32 s23, 2
	s_add_i32 s22, s22, 1
	s_branch .Lsqa_next

; __device__ __forceinline__ unsigned valkey(float f) { const unsigned b = __float_as_uint(f); return b ^ ((unsigned)((int)b >> 31) | 0x80000000u); }
; __device__ __forceinline__ void select_query(const unsigned (&u)[64], unsigned vmax, int q, int b, int lane, unsigned* MASKb) {
;     ...
;             const float frac = (it >= 9 && (it & 1)) ? 0.5f : Llo * __builtin_amdgcn_rcpf(Llo + Lhi);
;             unsigned mid = valkey(vlo + frac * (vhi - vlo));
;             if (mid <= lo) mid = lo + 1u;
;             if (mid >= hi) mid = hi - 1u;
;             mid = __builtin_amdgcn_readfirstlane(mid);
.Lsqa_frac:
	v_mov_b32_e32 v0, s16
	v_sub_f32_e32 v34, s17, v0
	v_fma_f32 v191, v191, v34, v0
	s_branch .Lsqa_key

; __device__ __forceinline__ float keyval(unsigned k) { return __uint_as_float((k & 0x80000000u) ? (k ^ 0x80000000u) : ~k); }
; __device__ __forceinline__ unsigned valkey(float f) { const unsigned b = __float_as_uint(f); return b ^ ((unsigned)((int)b >> 31) | 0x80000000u); }
; __device__ __forceinline__ void select_query(const unsigned (&u)[64], unsigned vmax, int q, int b, int lane, unsigned* MASKb) {
;     ...
;             if (hi - lo <= 1u) { T = lo; exact = false; break; }
;             const float vlo = keyval(lo), vhi = keyval(hi);
;             const float frac = (it >= 9 && (it & 1)) ? 0.5f : Llo * __builtin_amdgcn_rcpf(Llo + Lhi);
;             unsigned mid = valkey(vlo + frac * (vhi - vlo));
;             if (mid <= lo) mid = lo + 1u;
;             if (mid >= hi) mid = hi - 1u;
;             mid = __builtin_amdgcn_readfirstlane(mid);
;             const int c = count_ge(u, mid, nblk);
;             if (c == 256) { T = mid; exact = true; break; }
;             if (c > 256) { lo = mid; Llo = __log2f((float)c) - L256; if (last == 1) Lhi *= 0.5f; last = 1; }
;             else { hi = mid; Lhi = L256 - __log2f(fmaxf((float)c, 0.5f)); if (last == 2) Llo *= 0.5f; last = 2; }
.Lsqb_red:
	v_add_u32_e32 v138, v138, v140
	s_nop 1
	v_add_u32_dpp v138, v138, v138 row_shr:1 row_mask:0xf bank_mask:0xf bound_ctrl:1
	s_nop 1
	v_add_u32_dpp v138, v138, v138 row_shr:2 row_mask:0xf bank_mask:0xf bound_ctrl:1
	s_nop 1
	v_add_u32_dpp v138, v138, v138 row_shr:4 row_mask:0xf bank_mask:0xf bound_ctrl:1
	s_nop 1
	v_add_u32_dpp v138, v138, v138 row_shr:8 row_mask:0xf bank_mask:0xf bound_ctrl:1
	s_nop 1
	v_add_u32_dpp v138, v138, v138 row_bcast:15 row_mask:0xa bank_mask:0xf
	s_nop 1
	v_add_u32_dpp v138, v138, v138 row_bcast:31 row_mask:0xc bank_mask:0xf
	s_nop 0
	v_readlane_b32 s24, v138, 63
	s_cmp_lg_u32 s21, 2
	s_cbranch_scc1 .Lsqb_disp
	s_cmp_lg_u32 s99, 0
	s_cbranch_scc1 .Lsqb_st2
	s_cmpk_eq_i32 s24, 0x100
	s_cbranch_scc1 .Lsqb_exact
	v_cvt_f32_u32_e32 v142, s24
	s_cmpk_gt_i32 s24, 0x100
	s_cselect_b64 vcc, -1, 0
	v_max_f32_e32 v142, 0.5, v142
	s_cselect_b32 s13, s14, s13
	s_cselect_b32 s12, s12, s14
	v_log_f32_e32 v142, v142
	s_cselect_b32 s98, s24, s98
	s_cselect_b32 s15, s15, s24
	s_cselect_b32 s26, 1, 2
	v_cndmask_b32_e32 v76, v76, v146, vcc
	v_cndmask_b32_e32 v77, v146, v77, vcc
	s_cmp_eq_u32 s23, s26
	s_cselect_b32 s27, 0x3f400000, 1.0
	s_mov_b32 s23, s26
	s_add_i32 s22, s22, 1
	v_add_f32_e32 v138, 0xc1000b88, v142
	v_sub_f32_e32 v140, 0x41000b88, v142
	v_mul_f32_e32 v203, s27, v141
	v_mul_f32_e32 v204, s27, v139
	v_cndmask_b32_e32 v139, v204, v138, vcc
	v_cndmask_b32_e32 v141, v140, v203, vcc
.Lsqb_next:
	s_sub_u32 s26, s12, s13
	s_cmp_lt_u32 s26, 2
	s_cbranch_scc1 .Lsqb_collapse
	s_sub_u32 s26, s98, s15
	s_cmp_le_u32 s26, 4
	s_cbranch_scc1 .Lsqb_endg
	s_cmp_eq_u32 s101, 0
	s_cbranch_scc1 .Lsqb_lin
	s_cmp_lt_i32 s22, 9
	s_cbranch_scc0 .Lsqb_lin
	v_add_f32_e32 v142, v139, v141
	v_sub_f32_e32 v140, v77, v76
	v_rcp_f32_e32 v142, v142
	s_lshl_b32 s26, s99, 31
	v_mul_f32_e32 v142, v139, v142
	v_fma_f32 v146, v142, v140, v76
	v_log_f32_e32 v138, v146
	s_nop 0
	v_mul_f32_e32 v138, 0x3f2aaaab, v138
	v_exp_f32_e32 v142, v138
	s_nop 0
	v_xor_b32_e32 v142, s26, v142

; __device__ __forceinline__ void select_query(const unsigned (&u)[64], unsigned vmax, int q, int b, int lane, unsigned* MASKb) {
;     ...
;         const int cpos = count_ge(u, K0 + 1u, nblk);
;         if (cpos == 256) { T = K0 + 1u; exact = true; done = true; }
;         else if (cpos > 256) { lo = K0 + 1u; Llo = __log2f((float)cpos) - L256; hi = kmax + 1u; Lhi = L256 + 1.f; }
.Lsqb_disp:
	s_cmp_eq_u32 s21, 2
	s_cbranch_scc1 .Lsqb_st2
	s_cmp_eq_u32 s21, 1
	s_cbranch_scc1 .Lsqb_st1
	s_cmpk_eq_i32 s24, 0x100
	s_cbranch_scc1 .Lsqb_exact
	s_cmpk_gt_i32 s24, 0x100
	s_cbranch_scc0 .Lsqb_s0lt
	s_mov_b32 s13, 0x80000001
	s_add_i32 s12, s19, 1
	s_mov_b32 s15, 0
	v_cvt_f32_u32_e32 v139, s24
	v_log_f32_e32 v139, v139
	v_mov_b32_e32 v141, 0x41200b88
	v_add_f32_e32 v139, 0xc1000b88, v139
	s_and_b32 s26, s12, 0x7fffffff
	s_bfe_u32 s27, s26, 0x80017
	s_sub_u32 s27, s27, 0x43
	s_cmp_lt_u32 s27, 0x79
	s_cselect_b32 s101, 1, 0
	v_sqrt_f32_e32 v77, s26
	v_mov_b32_e32 v76, 0
	v_mul_f32_e32 v77, s26, v77
	s_mov_b32 s98, s24
	s_mov_b32 s99, 0
	s_mov_b32 s22, 0
	s_mov_b32 s23, 0
	s_mov_b32 s21, 2
	s_branch .Lsqb_next

; __device__ __forceinline__ unsigned valkey(float f) { const unsigned b = __float_as_uint(f); return b ^ ((unsigned)((int)b >> 31) | 0x80000000u); }
; __device__ __forceinline__ void select_query(const unsigned (&u)[64], unsigned vmax, int q, int b, int lane, unsigned* MASKb) {
;     ...
;             const float frac = (it >= 9 && (it & 1)) ? 0.5f : Llo * __builtin_amdgcn_rcpf(Llo + Lhi);
;             unsigned mid = valkey(vlo + frac * (vhi - vlo));
;             if (mid <= lo) mid = lo + 1u;
;             if (mid >= hi) mid = hi - 1u;
;             mid = __builtin_amdgcn_readfirstlane(mid);
.Lsqb_frac:
	v_mov_b32_e32 v138, s16
	v_sub_f32_e32 v140, s17, v138
	v_fma_f32 v142, v142, v140, v138
	s_branch .Lsqb_key
